# up-epilogue-group0-no-exit-wait-second-barrier-group0-only
# baseline (speedup 1.0000x reference)
; #define LAS __attribute__((address_space(3)))
; #define PG8_BAR __builtin_amdgcn_s_barrier()
;     __device__ __forceinline__ void operator()(f32x4 (&acc)[2][2][4][2], const Unit& u, int wr, int wc, int fr, int fq, LAS unsigned char* xl) const {
;     ...
;         if (fr >= 14) {
; #pragma unroll
;             for (int ai = 0; ai < 2; ++ai)
; #pragma unroll
;                 for (int s = 0; s < NS; ++s)
; #pragma unroll
;                     for (int n = 0; n < 2; ++n) *(LAS f32x4*)(bnd + (((ai * 2 + wr) * 2 + (fr - 14)) * 256 + s * 128 + chl + 4 * n)) = acc[ai][s][3][n];
;             if (wr == 1) {
; #pragma unroll
;                 for (int s = 0; s < NS; ++s)
; #pragma unroll
;                     for (int n = 0; n < 2; ++n) *(f32x4*)(TAIL + (size_t)(u.pm * 2 + (fr - 14)) * C + (s ? voff : 0) + ch0 + 4 * n) = acc[1][s][3][n];
;             }
;         }
;         asm volatile("s_waitcnt lgkmcnt(0)" ::: "memory"); PG8_BAR; asm volatile("" ::: "memory"); PG8_BAR; asm volatile("" ::: "memory");
;         u32x4 bgv[2][4];
;         if (MODE == 1) {
; #pragma unroll
;             for (int ai = 0; ai < 2; ++ai)
; #pragma unroll
;                 for (int m = 0; m < 4; ++m) bgv[ai][m] = *(const u32x4*)(BG + (size_t)(u.pm * BM + ai * HALF + wr * 64 + m * 16 + fr) * D + ch0);
;         }
; #pragma unroll
;         for (int s = 0; s < NS; ++s)
; #pragma unroll
;             for (int n = 0; n < 2; ++n) {
;                 const int lc = s * 128 + chl + 4 * n;
;                 const f32x4 w0 = *(const LAS f32x4*)(wt + lc), w1 = *(const LAS f32x4*)(wt + 256 + lc), w2 = *(const LAS f32x4*)(wt + 512 + lc), bb = *(const LAS f32x4*)(wt + 768 + lc);
; #pragma unroll
;                 for (int ai = 0; ai < 2; ++ai) {
;                     const int blk = ai * 2 + wr;
;                     f32x4 pg = (f32x4){0.f, 0.f, 0.f, 0.f};
;                     if (blk > 0) pg = *(const LAS f32x4*)(bnd + (((blk - 1) * 2 + (fr & 1)) * 256 + lc));
.LBB0_741:
	v_readfirstlane_b32 s48, v235
	s_waitcnt lgkmcnt(0)
	s_waitcnt vmcnt(16)
	v_or_b32_e32 v150, s8, v155
	s_and_saveexec_b64 s[8:9], s[4:5]
	s_cbranch_execz .LBB0_744
	s_andn2_b64 vcc, exec, s[2:3]
	ds_write_b128 v179, v[124:127]
	ds_write_b128 v179, v[96:99] offset:16
	ds_write_b128 v179, v[60:63] offset:512
	ds_write_b128 v179, v[28:31] offset:528
	ds_write_b128 v179, v[112:115] offset:4096
	ds_write_b128 v179, v[76:79] offset:4112
	ds_write_b128 v179, v[44:47] offset:4608
	ds_write_b128 v179, v[12:15] offset:4624
	s_cbranch_vccnz .LBB0_744
	v_lshl_add_u32 v130, s88, 1, v156
	v_mov_b64_e32 v[128:129], s[56:57]
	v_ashrrev_i32_e32 v151, 31, v150
	v_mad_i64_i32 v[128:129], s[0:1], v130, s20, v[128:129]
	v_lshl_add_u64 v[128:129], v[150:151], 2, v[128:129]
	s_mov_b64 s[0:1], 0x5800
	global_store_dwordx4 v[128:129], v[112:115], off
	global_store_dwordx4 v[128:129], v[76:79], off offset:16
	v_lshl_add_u64 v[130:131], v[128:129], 0, s[0:1]
	v_add_co_u32_e32 v128, vcc, 0x5000, v128
	s_nop 1
	v_addc_co_u32_e32 v129, vcc, 0, v129, vcc
	global_store_dwordx4 v[128:129], v[44:47], off offset:2048
	global_store_dwordx4 v[130:131], v[12:15], off offset:16
.LBB0_744:
	s_or_b64 exec, exec, s[8:9]
	s_waitcnt lgkmcnt(0)
	s_barrier
	s_cmpk_lt_u32 s48, 0x100
	s_cbranch_scc0 .Lup_bb_skip
	s_barrier
.Lup_bb_skip:
	ds_read_b128 v[128:131], v157
	ds_read_b128 v[132:135], v158
	ds_read_b128 v[136:139], v159
	ds_read_b128 v[140:143], v160
	v_mov_b32_e32 v144, 0
	s_and_b64 vcc, exec, s[60:61]
	v_mov_b32_e32 v146, 0
	v_mov_b32_e32 v147, 0
	v_mov_b32_e32 v148, 0
	v_mov_b32_e32 v149, 0
	s_cbranch_vccz .LBB0_746
	ds_read_b128 v[146:149], v183
